# EpiOut layer-0: adjacent 8-byte XB stores paired into one 16-byte store per lane (32 dwordx2 -> 16 dwordx4 per unit)
# speedup vs baseline: 1.0053x; 1.0053x over previous
.LBB0_1063:
	v_and_b32_e32 v144, 64, v224
	v_xor_b32_e32 v143, 16, v224
	v_add_u32_e32 v144, 64, v144
	v_cmp_lt_i32_e32 vcc, v143, v144
	v_lshl_add_u32 v142, s8, 8, v135
	s_lshl_b32 s0, s7, 8
	v_cndmask_b32_e32 v143, v224, v143, vcc
	v_lshlrev_b32_e32 v149, 2, v143
	v_xor_b32_e32 v143, 32, v224
	v_cmp_lt_i32_e32 vcc, v143, v144
	s_ashr_i32 s1, s0, 31
	v_mov_b32_e32 v141, s1
	v_cndmask_b32_e32 v143, v224, v143, vcc
	v_lshlrev_b32_e32 v148, 2, v143
	v_ashrrev_i32_e32 v143, 31, v142
	v_or_b32_e32 v140, s0, v134
	v_lshlrev_b64 v[144:145], 10, v[142:143]
	v_lshl_add_u64 v[154:155], v[144:145], 0, v[140:141]
	v_readlane_b32 s76, v252, 6
	v_lshlrev_b64 v[156:157], 2, v[154:155]
	v_readlane_b32 s77, v252, 7
	s_lshl_b32 s0, s7, 2
	s_ashr_i32 s1, s0, 31
	v_lshl_add_u64 v[144:145], s[76:77], 0, v[156:157]
	global_load_dwordx4 v[150:153], v[144:145], off
	v_readlane_b32 s78, v252, 8
	v_readlane_b32 s79, v252, 9
	v_readlane_b32 s80, v252, 10
	v_readlane_b32 s81, v252, 11
	v_readlane_b32 s82, v252, 12
	v_readlane_b32 s83, v252, 13
	v_readlane_b32 s84, v252, 14
	v_readlane_b32 s85, v252, 15
	v_readlane_b32 s86, v252, 16
	v_readlane_b32 s87, v252, 17
	v_readlane_b32 s88, v252, 18
	v_readlane_b32 s89, v252, 19
	v_readlane_b32 s90, v252, 20
	v_readlane_b32 s91, v252, 21
	s_waitcnt vmcnt(0)
	v_pk_add_f32 v[152:153], v[126:127], v[152:153]
	v_pk_add_f32 v[150:151], v[124:125], v[150:151]
	v_lshl_add_u64 v[124:125], s[56:57], 0, v[156:157]
	global_store_dwordx4 v[124:125], v[150:153], off
	v_cvt_pk_bf16_f32 v160, v150, v151
	v_lshlrev_b64 v[126:127], 1, v[154:155]
	v_mul_f32_e32 v151, v151, v151
	v_cvt_pk_bf16_f32 v161, v152, v153
	v_lshl_add_u64 v[154:155], s[62:63], 0, v[126:127]
	v_fmac_f32_e32 v151, v150, v150
	v_mul_f32_e32 v150, v153, v153
	v_fmac_f32_e32 v150, v152, v152
	v_add_f32_e32 v154, v151, v150
	global_load_dwordx4 v[150:153], v[144:145], off offset:16
	s_waitcnt vmcnt(0)
	v_pk_add_f32 v[122:123], v[122:123], v[152:153]
	v_pk_add_f32 v[120:121], v[120:121], v[150:151]
	global_store_dwordx4 v[124:125], v[120:123], off offset:16
	v_cvt_pk_bf16_f32 v162, v120, v121
	v_or_b32_e32 v152, 8, v126
	v_mul_f32_e32 v121, v121, v121
	v_mov_b32_e32 v153, v127
	v_fmac_f32_e32 v121, v120, v120
	v_mul_f32_e32 v120, v123, v123
	v_cvt_pk_bf16_f32 v163, v122, v123
	v_lshl_add_u64 v[152:153], s[62:63], 0, v[152:153]
	v_fmac_f32_e32 v120, v122, v122
	global_store_dwordx4 v[152:153], v[160:163], off offset:-8
	v_add_f32_e32 v120, v121, v120
	v_add_f32_e32 v150, v154, v120
	global_load_dwordx4 v[120:123], v[144:145], off offset:512
	s_waitcnt vmcnt(0)
	v_pk_add_f32 v[118:119], v[118:119], v[122:123]
	v_pk_add_f32 v[116:117], v[116:117], v[120:121]
	global_store_dwordx4 v[124:125], v[116:119], off offset:512
	v_cvt_pk_bf16_f32 v164, v116, v117
	v_or_b32_e32 v122, 0x100, v126
	v_mul_f32_e32 v117, v117, v117
	v_mov_b32_e32 v123, v127
	v_fmac_f32_e32 v117, v116, v116
	v_mul_f32_e32 v116, v119, v119
	v_cvt_pk_bf16_f32 v165, v118, v119
	v_lshl_add_u64 v[122:123], s[62:63], 0, v[122:123]
	v_fmac_f32_e32 v116, v118, v118
	v_add_f32_e32 v116, v117, v116
	v_add_f32_e32 v120, v150, v116
	global_load_dwordx4 v[116:119], v[144:145], off offset:528
	v_or_b32_e32 v126, 0x108, v126
	s_waitcnt vmcnt(0)
	v_pk_add_f32 v[114:115], v[114:115], v[118:119]
	v_pk_add_f32 v[112:113], v[112:113], v[116:117]
	global_store_dwordx4 v[124:125], v[112:115], off offset:528
	v_cvt_pk_bf16_f32 v166, v112, v113
	v_cvt_pk_bf16_f32 v167, v114, v115
	v_mul_f32_e32 v113, v113, v113
	v_fmac_f32_e32 v113, v112, v112
	v_mul_f32_e32 v112, v115, v115
	v_fmac_f32_e32 v112, v114, v114
	v_add_f32_e32 v112, v113, v112
	v_add_f32_e32 v112, v120, v112
	ds_bpermute_b32 v113, v149, v112
	v_lshl_add_u64 v[118:119], s[62:63], 0, v[126:127]
	global_store_dwordx4 v[118:119], v[164:167], off offset:-8
	s_waitcnt lgkmcnt(0)
	v_add_f32_e32 v112, v112, v113
	ds_bpermute_b32 v113, v148, v112
	s_and_saveexec_b64 s[46:47], s[36:37]
	s_cbranch_execz .LBB0_1065
	v_lshlrev_b64 v[114:115], 6, v[142:143]
	v_lshl_add_u64 v[114:115], s[54:55], 0, v[114:115]
	v_lshl_add_u64 v[114:115], s[0:1], 2, v[114:115]
	s_lshl_b32 s92, s18, 2
	v_lshl_add_u64 v[114:115], v[114:115], 0, s[92:93]
	s_waitcnt lgkmcnt(0)
	v_add_f32_e32 v112, v112, v113
	global_store_dword v[114:115], v112, off
.LBB0_1065:
	s_or_b64 exec, exec, s[46:47]
	v_or_b32_e32 v112, 16, v142
	s_waitcnt lgkmcnt(0)
	v_ashrrev_i32_e32 v113, 31, v112
	v_lshlrev_b64 v[114:115], 10, v[112:113]
	v_lshl_add_u64 v[120:121], v[114:115], 0, v[140:141]
	v_readlane_b32 s76, v252, 6
	v_lshlrev_b64 v[122:123], 2, v[120:121]
	v_readlane_b32 s77, v252, 7
	v_readlane_b32 s78, v252, 8
	v_readlane_b32 s79, v252, 9
	v_lshl_add_u64 v[114:115], s[76:77], 0, v[122:123]
	global_load_dwordx4 v[116:119], v[114:115], off
	v_readlane_b32 s80, v252, 10
	v_readlane_b32 s81, v252, 11
	v_readlane_b32 s82, v252, 12
	v_readlane_b32 s83, v252, 13
	v_readlane_b32 s84, v252, 14
	v_readlane_b32 s85, v252, 15
	v_readlane_b32 s86, v252, 16
	v_readlane_b32 s87, v252, 17
	v_readlane_b32 s88, v252, 18
	v_readlane_b32 s89, v252, 19
	v_readlane_b32 s90, v252, 20
	v_readlane_b32 s91, v252, 21
	s_waitcnt vmcnt(0)
	v_pk_add_f32 v[118:119], v[110:111], v[118:119]
	v_pk_add_f32 v[116:117], v[108:109], v[116:117]
	v_lshl_add_u64 v[108:109], s[56:57], 0, v[122:123]
	global_store_dwordx4 v[108:109], v[116:119], off
	v_cvt_pk_bf16_f32 v160, v116, v117
	v_lshlrev_b64 v[110:111], 1, v[120:121]
	v_mul_f32_e32 v117, v117, v117
	v_cvt_pk_bf16_f32 v161, v118, v119
	v_lshl_add_u64 v[120:121], s[62:63], 0, v[110:111]
	v_fmac_f32_e32 v117, v116, v116
	v_mul_f32_e32 v116, v119, v119
	v_fmac_f32_e32 v116, v118, v118
	v_add_f32_e32 v120, v117, v116
	global_load_dwordx4 v[116:119], v[114:115], off offset:16
	s_waitcnt vmcnt(0)
	v_pk_add_f32 v[106:107], v[106:107], v[118:119]
	v_pk_add_f32 v[104:105], v[104:105], v[116:117]
	global_store_dwordx4 v[108:109], v[104:107], off offset:16
	v_cvt_pk_bf16_f32 v162, v104, v105
	v_or_b32_e32 v118, 8, v110
	v_mul_f32_e32 v105, v105, v105
	v_mov_b32_e32 v119, v111
	v_fmac_f32_e32 v105, v104, v104
	v_mul_f32_e32 v104, v107, v107
	v_cvt_pk_bf16_f32 v163, v106, v107
	v_lshl_add_u64 v[118:119], s[62:63], 0, v[118:119]
	v_fmac_f32_e32 v104, v106, v106
	global_store_dwordx4 v[118:119], v[160:163], off offset:-8
	v_add_f32_e32 v104, v105, v104
	v_add_f32_e32 v116, v120, v104
	global_load_dwordx4 v[104:107], v[114:115], off offset:512
	s_waitcnt vmcnt(0)
	v_pk_add_f32 v[102:103], v[102:103], v[106:107]
	v_pk_add_f32 v[100:101], v[100:101], v[104:105]
	global_store_dwordx4 v[108:109], v[100:103], off offset:512
	v_cvt_pk_bf16_f32 v164, v100, v101
	v_or_b32_e32 v106, 0x100, v110
	v_mul_f32_e32 v101, v101, v101
	v_mov_b32_e32 v107, v111
	v_fmac_f32_e32 v101, v100, v100
	v_mul_f32_e32 v100, v103, v103
	v_cvt_pk_bf16_f32 v165, v102, v103
	v_lshl_add_u64 v[106:107], s[62:63], 0, v[106:107]
	v_fmac_f32_e32 v100, v102, v102
	v_add_f32_e32 v100, v101, v100
	v_add_f32_e32 v104, v116, v100
	global_load_dwordx4 v[100:103], v[114:115], off offset:528
	v_or_b32_e32 v110, 0x108, v110
	s_waitcnt vmcnt(0)
	v_pk_add_f32 v[98:99], v[98:99], v[102:103]
	v_pk_add_f32 v[96:97], v[96:97], v[100:101]
	global_store_dwordx4 v[108:109], v[96:99], off offset:528
	v_cvt_pk_bf16_f32 v166, v96, v97
	v_cvt_pk_bf16_f32 v167, v98, v99
	v_mul_f32_e32 v97, v97, v97
	v_fmac_f32_e32 v97, v96, v96
	v_mul_f32_e32 v96, v99, v99
	v_fmac_f32_e32 v96, v98, v98
	v_add_f32_e32 v96, v97, v96
	v_add_f32_e32 v96, v104, v96
	ds_bpermute_b32 v97, v149, v96
	v_lshl_add_u64 v[102:103], s[62:63], 0, v[110:111]
	global_store_dwordx4 v[102:103], v[164:167], off offset:-8
	s_waitcnt lgkmcnt(0)
	v_add_f32_e32 v96, v96, v97
	ds_bpermute_b32 v97, v148, v96
	s_and_saveexec_b64 s[46:47], s[36:37]
	s_cbranch_execz .LBB0_1067
	v_lshlrev_b64 v[98:99], 6, v[112:113]
	v_lshl_add_u64 v[98:99], s[54:55], 0, v[98:99]
	v_lshl_add_u64 v[98:99], s[0:1], 2, v[98:99]
	s_lshl_b32 s92, s18, 2
	v_lshl_add_u64 v[98:99], v[98:99], 0, s[92:93]
	s_waitcnt lgkmcnt(0)
	v_add_f32_e32 v96, v96, v97
	global_store_dword v[98:99], v96, off
.LBB0_1067:
	s_or_b64 exec, exec, s[46:47]
	v_or_b32_e32 v96, 32, v142
	s_waitcnt lgkmcnt(0)
	v_ashrrev_i32_e32 v97, 31, v96
	v_lshlrev_b64 v[98:99], 10, v[96:97]
	v_lshl_add_u64 v[104:105], v[98:99], 0, v[140:141]
	v_readlane_b32 s76, v252, 6
	v_lshlrev_b64 v[106:107], 2, v[104:105]
	v_readlane_b32 s77, v252, 7
	v_readlane_b32 s78, v252, 8
	v_readlane_b32 s79, v252, 9
	v_lshl_add_u64 v[98:99], s[76:77], 0, v[106:107]
	global_load_dwordx4 v[100:103], v[98:99], off
	v_readlane_b32 s80, v252, 10
	v_readlane_b32 s81, v252, 11
	v_readlane_b32 s82, v252, 12
	v_readlane_b32 s83, v252, 13
	v_readlane_b32 s84, v252, 14
	v_readlane_b32 s85, v252, 15
	v_readlane_b32 s86, v252, 16
	v_readlane_b32 s87, v252, 17
	v_readlane_b32 s88, v252, 18
	v_readlane_b32 s89, v252, 19
	v_readlane_b32 s90, v252, 20
	v_readlane_b32 s91, v252, 21
	s_waitcnt vmcnt(0)
	v_pk_add_f32 v[102:103], v[94:95], v[102:103]
	v_pk_add_f32 v[100:101], v[92:93], v[100:101]
	v_lshl_add_u64 v[92:93], s[56:57], 0, v[106:107]
	global_store_dwordx4 v[92:93], v[100:103], off
	v_cvt_pk_bf16_f32 v160, v100, v101
	v_lshlrev_b64 v[94:95], 1, v[104:105]
	v_mul_f32_e32 v101, v101, v101
	v_cvt_pk_bf16_f32 v161, v102, v103
	v_lshl_add_u64 v[104:105], s[62:63], 0, v[94:95]
	v_fmac_f32_e32 v101, v100, v100
	v_mul_f32_e32 v100, v103, v103
	v_fmac_f32_e32 v100, v102, v102
	v_add_f32_e32 v104, v101, v100
	global_load_dwordx4 v[100:103], v[98:99], off offset:16
	s_waitcnt vmcnt(0)
	v_pk_add_f32 v[90:91], v[90:91], v[102:103]
	v_pk_add_f32 v[88:89], v[88:89], v[100:101]
	global_store_dwordx4 v[92:93], v[88:91], off offset:16
	v_cvt_pk_bf16_f32 v162, v88, v89
	v_or_b32_e32 v102, 8, v94
	v_mul_f32_e32 v89, v89, v89
	v_mov_b32_e32 v103, v95
	v_fmac_f32_e32 v89, v88, v88
	v_mul_f32_e32 v88, v91, v91
	v_cvt_pk_bf16_f32 v163, v90, v91
	v_lshl_add_u64 v[102:103], s[62:63], 0, v[102:103]
	v_fmac_f32_e32 v88, v90, v90
	global_store_dwordx4 v[102:103], v[160:163], off offset:-8
	v_add_f32_e32 v88, v89, v88
	v_add_f32_e32 v100, v104, v88
	global_load_dwordx4 v[88:91], v[98:99], off offset:512
	s_waitcnt vmcnt(0)
	v_pk_add_f32 v[86:87], v[86:87], v[90:91]
	v_pk_add_f32 v[84:85], v[84:85], v[88:89]
	global_store_dwordx4 v[92:93], v[84:87], off offset:512
	v_cvt_pk_bf16_f32 v164, v84, v85
	v_or_b32_e32 v90, 0x100, v94
	v_mul_f32_e32 v85, v85, v85
	v_mov_b32_e32 v91, v95
	v_fmac_f32_e32 v85, v84, v84
	v_mul_f32_e32 v84, v87, v87
	v_cvt_pk_bf16_f32 v165, v86, v87
	v_lshl_add_u64 v[90:91], s[62:63], 0, v[90:91]
	v_fmac_f32_e32 v84, v86, v86
	v_add_f32_e32 v84, v85, v84
	v_add_f32_e32 v88, v100, v84
	global_load_dwordx4 v[84:87], v[98:99], off offset:528
	v_or_b32_e32 v94, 0x108, v94
	s_waitcnt vmcnt(0)
	v_pk_add_f32 v[82:83], v[82:83], v[86:87]
	v_pk_add_f32 v[80:81], v[80:81], v[84:85]
	global_store_dwordx4 v[92:93], v[80:83], off offset:528
	v_cvt_pk_bf16_f32 v166, v80, v81
	v_cvt_pk_bf16_f32 v167, v82, v83
	v_mul_f32_e32 v81, v81, v81
	v_fmac_f32_e32 v81, v80, v80
	v_mul_f32_e32 v80, v83, v83
	v_fmac_f32_e32 v80, v82, v82
	v_add_f32_e32 v80, v81, v80
	v_add_f32_e32 v80, v88, v80
	ds_bpermute_b32 v81, v149, v80
	v_lshl_add_u64 v[86:87], s[62:63], 0, v[94:95]
	global_store_dwordx4 v[86:87], v[164:167], off offset:-8
	s_waitcnt lgkmcnt(0)
	v_add_f32_e32 v80, v80, v81
	ds_bpermute_b32 v81, v148, v80
	s_and_saveexec_b64 s[46:47], s[36:37]
	s_cbranch_execz .LBB0_1069
	v_lshlrev_b64 v[82:83], 6, v[96:97]
	v_lshl_add_u64 v[82:83], s[54:55], 0, v[82:83]
	v_lshl_add_u64 v[82:83], s[0:1], 2, v[82:83]
	s_lshl_b32 s92, s18, 2
	v_lshl_add_u64 v[82:83], v[82:83], 0, s[92:93]
	s_waitcnt lgkmcnt(0)
	v_add_f32_e32 v80, v80, v81
	global_store_dword v[82:83], v80, off
.LBB0_1069:
	s_or_b64 exec, exec, s[46:47]
	v_or_b32_e32 v80, 48, v142
	s_waitcnt lgkmcnt(0)
	v_ashrrev_i32_e32 v81, 31, v80
	v_lshlrev_b64 v[82:83], 10, v[80:81]
	v_lshl_add_u64 v[88:89], v[82:83], 0, v[140:141]
	v_readlane_b32 s76, v252, 6
	v_lshlrev_b64 v[90:91], 2, v[88:89]
	v_readlane_b32 s77, v252, 7
	v_readlane_b32 s78, v252, 8
	v_readlane_b32 s79, v252, 9
	v_lshl_add_u64 v[82:83], s[76:77], 0, v[90:91]
	global_load_dwordx4 v[84:87], v[82:83], off
	v_readlane_b32 s80, v252, 10
	v_readlane_b32 s81, v252, 11
	v_readlane_b32 s82, v252, 12
	v_readlane_b32 s83, v252, 13
	v_readlane_b32 s84, v252, 14
	v_readlane_b32 s85, v252, 15
	v_readlane_b32 s86, v252, 16
	v_readlane_b32 s87, v252, 17
	v_readlane_b32 s88, v252, 18
	v_readlane_b32 s89, v252, 19
	v_readlane_b32 s90, v252, 20
	v_readlane_b32 s91, v252, 21
	s_waitcnt vmcnt(0)
	v_pk_add_f32 v[86:87], v[78:79], v[86:87]
	v_pk_add_f32 v[84:85], v[76:77], v[84:85]
	v_lshl_add_u64 v[76:77], s[56:57], 0, v[90:91]
	global_store_dwordx4 v[76:77], v[84:87], off
	v_cvt_pk_bf16_f32 v160, v84, v85
	v_lshlrev_b64 v[78:79], 1, v[88:89]
	v_mul_f32_e32 v85, v85, v85
	v_cvt_pk_bf16_f32 v161, v86, v87
	v_lshl_add_u64 v[88:89], s[62:63], 0, v[78:79]
	v_fmac_f32_e32 v85, v84, v84
	v_mul_f32_e32 v84, v87, v87
	v_fmac_f32_e32 v84, v86, v86
	v_add_f32_e32 v88, v85, v84
	global_load_dwordx4 v[84:87], v[82:83], off offset:16
	s_waitcnt vmcnt(0)
	v_pk_add_f32 v[74:75], v[74:75], v[86:87]
	v_pk_add_f32 v[72:73], v[72:73], v[84:85]
	global_store_dwordx4 v[76:77], v[72:75], off offset:16
	v_cvt_pk_bf16_f32 v162, v72, v73
	v_or_b32_e32 v86, 8, v78
	v_mul_f32_e32 v73, v73, v73
	v_mov_b32_e32 v87, v79
	v_fmac_f32_e32 v73, v72, v72
	v_mul_f32_e32 v72, v75, v75
	v_cvt_pk_bf16_f32 v163, v74, v75
	v_lshl_add_u64 v[86:87], s[62:63], 0, v[86:87]
	v_fmac_f32_e32 v72, v74, v74
	global_store_dwordx4 v[86:87], v[160:163], off offset:-8
	v_add_f32_e32 v72, v73, v72
	v_add_f32_e32 v84, v88, v72
	global_load_dwordx4 v[72:75], v[82:83], off offset:512
	s_waitcnt vmcnt(0)
	v_pk_add_f32 v[70:71], v[70:71], v[74:75]
	v_pk_add_f32 v[68:69], v[68:69], v[72:73]
	global_store_dwordx4 v[76:77], v[68:71], off offset:512
	v_cvt_pk_bf16_f32 v164, v68, v69
	v_or_b32_e32 v74, 0x100, v78
	v_mul_f32_e32 v69, v69, v69
	v_mov_b32_e32 v75, v79
	v_fmac_f32_e32 v69, v68, v68
	v_mul_f32_e32 v68, v71, v71
	v_cvt_pk_bf16_f32 v165, v70, v71
	v_lshl_add_u64 v[74:75], s[62:63], 0, v[74:75]
	v_fmac_f32_e32 v68, v70, v70
	v_add_f32_e32 v68, v69, v68
	v_add_f32_e32 v72, v84, v68
	global_load_dwordx4 v[68:71], v[82:83], off offset:528
	v_or_b32_e32 v78, 0x108, v78
	s_waitcnt vmcnt(0)
	v_pk_add_f32 v[66:67], v[66:67], v[70:71]
	v_pk_add_f32 v[64:65], v[64:65], v[68:69]
	global_store_dwordx4 v[76:77], v[64:67], off offset:528
	v_cvt_pk_bf16_f32 v166, v64, v65
	v_cvt_pk_bf16_f32 v167, v66, v67
	v_mul_f32_e32 v65, v65, v65
	v_fmac_f32_e32 v65, v64, v64
	v_mul_f32_e32 v64, v67, v67
	v_fmac_f32_e32 v64, v66, v66
	v_add_f32_e32 v64, v65, v64
	v_add_f32_e32 v64, v72, v64
	ds_bpermute_b32 v65, v149, v64
	v_lshl_add_u64 v[70:71], s[62:63], 0, v[78:79]
	global_store_dwordx4 v[70:71], v[164:167], off offset:-8
	s_waitcnt lgkmcnt(0)
	v_add_f32_e32 v64, v64, v65
	ds_bpermute_b32 v65, v148, v64
	s_and_saveexec_b64 s[46:47], s[36:37]
	s_cbranch_execz .LBB0_1071
	v_lshlrev_b64 v[66:67], 6, v[80:81]
	v_lshl_add_u64 v[66:67], s[54:55], 0, v[66:67]
	v_lshl_add_u64 v[66:67], s[0:1], 2, v[66:67]
	s_lshl_b32 s92, s18, 2
	v_lshl_add_u64 v[66:67], v[66:67], 0, s[92:93]
	s_waitcnt lgkmcnt(0)
	v_add_f32_e32 v64, v64, v65
	global_store_dword v[66:67], v64, off
.LBB0_1071:
	s_or_b64 exec, exec, s[46:47]
	v_add_u32_e32 v64, 0x80, v142
	s_waitcnt lgkmcnt(0)
	v_ashrrev_i32_e32 v65, 31, v64
	v_lshlrev_b64 v[66:67], 10, v[64:65]
	v_lshl_add_u64 v[72:73], v[66:67], 0, v[140:141]
	v_readlane_b32 s76, v252, 6
	v_lshlrev_b64 v[74:75], 2, v[72:73]
	v_readlane_b32 s77, v252, 7
	v_readlane_b32 s78, v252, 8
	v_readlane_b32 s79, v252, 9
	v_lshl_add_u64 v[66:67], s[76:77], 0, v[74:75]
	global_load_dwordx4 v[68:71], v[66:67], off
	v_readlane_b32 s80, v252, 10
	v_readlane_b32 s81, v252, 11
	v_readlane_b32 s82, v252, 12
	v_readlane_b32 s83, v252, 13
	v_readlane_b32 s84, v252, 14
	v_readlane_b32 s85, v252, 15
	v_readlane_b32 s86, v252, 16
	v_readlane_b32 s87, v252, 17
	v_readlane_b32 s88, v252, 18
	v_readlane_b32 s89, v252, 19
	v_readlane_b32 s90, v252, 20
	v_readlane_b32 s91, v252, 21
	s_waitcnt vmcnt(0)
	v_pk_add_f32 v[70:71], v[62:63], v[70:71]
	v_pk_add_f32 v[68:69], v[60:61], v[68:69]
	v_lshl_add_u64 v[60:61], s[56:57], 0, v[74:75]
	global_store_dwordx4 v[60:61], v[68:71], off
	v_cvt_pk_bf16_f32 v160, v68, v69
	v_lshlrev_b64 v[62:63], 1, v[72:73]
	v_mul_f32_e32 v69, v69, v69
	v_cvt_pk_bf16_f32 v161, v70, v71
	v_lshl_add_u64 v[72:73], s[62:63], 0, v[62:63]
	v_fmac_f32_e32 v69, v68, v68
	v_mul_f32_e32 v68, v71, v71
	v_fmac_f32_e32 v68, v70, v70
	v_add_f32_e32 v72, v69, v68
	global_load_dwordx4 v[68:71], v[66:67], off offset:16
	s_waitcnt vmcnt(0)
	v_pk_add_f32 v[58:59], v[58:59], v[70:71]
	v_pk_add_f32 v[56:57], v[56:57], v[68:69]
	global_store_dwordx4 v[60:61], v[56:59], off offset:16
	v_cvt_pk_bf16_f32 v162, v56, v57
	v_or_b32_e32 v70, 8, v62
	v_mul_f32_e32 v57, v57, v57
	v_mov_b32_e32 v71, v63
	v_fmac_f32_e32 v57, v56, v56
	v_mul_f32_e32 v56, v59, v59
	v_cvt_pk_bf16_f32 v163, v58, v59
	v_lshl_add_u64 v[70:71], s[62:63], 0, v[70:71]
	v_fmac_f32_e32 v56, v58, v58
	global_store_dwordx4 v[70:71], v[160:163], off offset:-8
	v_add_f32_e32 v56, v57, v56
	v_add_f32_e32 v68, v72, v56
	global_load_dwordx4 v[56:59], v[66:67], off offset:512
	s_waitcnt vmcnt(0)
	v_pk_add_f32 v[54:55], v[54:55], v[58:59]
	v_pk_add_f32 v[52:53], v[52:53], v[56:57]
	global_store_dwordx4 v[60:61], v[52:55], off offset:512
	v_cvt_pk_bf16_f32 v164, v52, v53
	v_or_b32_e32 v58, 0x100, v62
	v_mul_f32_e32 v53, v53, v53
	v_mov_b32_e32 v59, v63
	v_fmac_f32_e32 v53, v52, v52
	v_mul_f32_e32 v52, v55, v55
	v_cvt_pk_bf16_f32 v165, v54, v55
	v_lshl_add_u64 v[58:59], s[62:63], 0, v[58:59]
	v_fmac_f32_e32 v52, v54, v54
	v_add_f32_e32 v52, v53, v52
	v_add_f32_e32 v56, v68, v52
	global_load_dwordx4 v[52:55], v[66:67], off offset:528
	v_or_b32_e32 v62, 0x108, v62
	s_waitcnt vmcnt(0)
	v_pk_add_f32 v[50:51], v[50:51], v[54:55]
	v_pk_add_f32 v[48:49], v[48:49], v[52:53]
	global_store_dwordx4 v[60:61], v[48:51], off offset:528
	v_cvt_pk_bf16_f32 v166, v48, v49
	v_cvt_pk_bf16_f32 v167, v50, v51
	v_mul_f32_e32 v49, v49, v49
	v_fmac_f32_e32 v49, v48, v48
	v_mul_f32_e32 v48, v51, v51
	v_fmac_f32_e32 v48, v50, v50
	v_add_f32_e32 v48, v49, v48
	v_add_f32_e32 v48, v56, v48
	ds_bpermute_b32 v49, v149, v48
	v_lshl_add_u64 v[54:55], s[62:63], 0, v[62:63]
	global_store_dwordx4 v[54:55], v[164:167], off offset:-8
	s_waitcnt lgkmcnt(0)
	v_add_f32_e32 v48, v48, v49
	ds_bpermute_b32 v49, v148, v48
	s_and_saveexec_b64 s[46:47], s[36:37]
	s_cbranch_execz .LBB0_1073
	v_lshlrev_b64 v[50:51], 6, v[64:65]
	v_lshl_add_u64 v[50:51], s[54:55], 0, v[50:51]
	v_lshl_add_u64 v[50:51], s[0:1], 2, v[50:51]
	s_lshl_b32 s92, s18, 2
	v_lshl_add_u64 v[50:51], v[50:51], 0, s[92:93]
	s_waitcnt lgkmcnt(0)
	v_add_f32_e32 v48, v48, v49
	global_store_dword v[50:51], v48, off
.LBB0_1073:
	s_or_b64 exec, exec, s[46:47]
	v_add_u32_e32 v48, 0x90, v142
	s_waitcnt lgkmcnt(0)
	v_ashrrev_i32_e32 v49, 31, v48
	v_lshlrev_b64 v[50:51], 10, v[48:49]
	v_lshl_add_u64 v[56:57], v[50:51], 0, v[140:141]
	v_readlane_b32 s76, v252, 6
	v_lshlrev_b64 v[58:59], 2, v[56:57]
	v_readlane_b32 s77, v252, 7
	v_readlane_b32 s78, v252, 8
	v_readlane_b32 s79, v252, 9
	v_lshl_add_u64 v[50:51], s[76:77], 0, v[58:59]
	global_load_dwordx4 v[52:55], v[50:51], off
	v_readlane_b32 s80, v252, 10
	v_readlane_b32 s81, v252, 11
	v_readlane_b32 s82, v252, 12
	v_readlane_b32 s83, v252, 13
	v_readlane_b32 s84, v252, 14
	v_readlane_b32 s85, v252, 15
	v_readlane_b32 s86, v252, 16
	v_readlane_b32 s87, v252, 17
	v_readlane_b32 s88, v252, 18
	v_readlane_b32 s89, v252, 19
	v_readlane_b32 s90, v252, 20
	v_readlane_b32 s91, v252, 21
	s_waitcnt vmcnt(0)
	v_pk_add_f32 v[54:55], v[46:47], v[54:55]
	v_pk_add_f32 v[52:53], v[44:45], v[52:53]
	v_lshl_add_u64 v[44:45], s[56:57], 0, v[58:59]
	global_store_dwordx4 v[44:45], v[52:55], off
	v_cvt_pk_bf16_f32 v160, v52, v53
	v_lshlrev_b64 v[46:47], 1, v[56:57]
	v_mul_f32_e32 v53, v53, v53
	v_cvt_pk_bf16_f32 v161, v54, v55
	v_lshl_add_u64 v[56:57], s[62:63], 0, v[46:47]
	v_fmac_f32_e32 v53, v52, v52
	v_mul_f32_e32 v52, v55, v55
	v_fmac_f32_e32 v52, v54, v54
	v_add_f32_e32 v56, v53, v52
	global_load_dwordx4 v[52:55], v[50:51], off offset:16
	s_waitcnt vmcnt(0)
	v_pk_add_f32 v[42:43], v[42:43], v[54:55]
	v_pk_add_f32 v[40:41], v[40:41], v[52:53]
	global_store_dwordx4 v[44:45], v[40:43], off offset:16
	v_cvt_pk_bf16_f32 v162, v40, v41
	v_or_b32_e32 v54, 8, v46
	v_mul_f32_e32 v41, v41, v41
	v_mov_b32_e32 v55, v47
	v_fmac_f32_e32 v41, v40, v40
	v_mul_f32_e32 v40, v43, v43
	v_cvt_pk_bf16_f32 v163, v42, v43
	v_lshl_add_u64 v[54:55], s[62:63], 0, v[54:55]
	v_fmac_f32_e32 v40, v42, v42
	global_store_dwordx4 v[54:55], v[160:163], off offset:-8
	v_add_f32_e32 v40, v41, v40
	v_add_f32_e32 v52, v56, v40
	global_load_dwordx4 v[40:43], v[50:51], off offset:512
	s_waitcnt vmcnt(0)
	v_pk_add_f32 v[38:39], v[38:39], v[42:43]
	v_pk_add_f32 v[36:37], v[36:37], v[40:41]
	global_store_dwordx4 v[44:45], v[36:39], off offset:512
	v_cvt_pk_bf16_f32 v164, v36, v37
	v_or_b32_e32 v42, 0x100, v46
	v_mul_f32_e32 v37, v37, v37
	v_mov_b32_e32 v43, v47
	v_fmac_f32_e32 v37, v36, v36
	v_mul_f32_e32 v36, v39, v39
	v_cvt_pk_bf16_f32 v165, v38, v39
	v_lshl_add_u64 v[42:43], s[62:63], 0, v[42:43]
	v_fmac_f32_e32 v36, v38, v38
	v_add_f32_e32 v36, v37, v36
	v_add_f32_e32 v40, v52, v36
	global_load_dwordx4 v[36:39], v[50:51], off offset:528
	v_or_b32_e32 v46, 0x108, v46
	s_waitcnt vmcnt(0)
	v_pk_add_f32 v[34:35], v[34:35], v[38:39]
	v_pk_add_f32 v[32:33], v[32:33], v[36:37]
	global_store_dwordx4 v[44:45], v[32:35], off offset:528
	v_cvt_pk_bf16_f32 v166, v32, v33
	v_cvt_pk_bf16_f32 v167, v34, v35
	v_mul_f32_e32 v33, v33, v33
	v_fmac_f32_e32 v33, v32, v32
	v_mul_f32_e32 v32, v35, v35
	v_fmac_f32_e32 v32, v34, v34
	v_add_f32_e32 v32, v33, v32
	v_add_f32_e32 v32, v40, v32
	ds_bpermute_b32 v33, v149, v32
	v_lshl_add_u64 v[38:39], s[62:63], 0, v[46:47]
	global_store_dwordx4 v[38:39], v[164:167], off offset:-8
	s_waitcnt lgkmcnt(0)
	v_add_f32_e32 v32, v32, v33
	ds_bpermute_b32 v33, v148, v32
	s_and_saveexec_b64 s[46:47], s[36:37]
	s_cbranch_execz .LBB0_1075
	v_lshlrev_b64 v[34:35], 6, v[48:49]
	v_lshl_add_u64 v[34:35], s[54:55], 0, v[34:35]
	v_lshl_add_u64 v[34:35], s[0:1], 2, v[34:35]
	s_lshl_b32 s92, s18, 2
	v_lshl_add_u64 v[34:35], v[34:35], 0, s[92:93]
	s_waitcnt lgkmcnt(0)
	v_add_f32_e32 v32, v32, v33
	global_store_dword v[34:35], v32, off
.LBB0_1075:
	s_or_b64 exec, exec, s[46:47]
	v_add_u32_e32 v32, 0xa0, v142
	s_waitcnt lgkmcnt(0)
	v_ashrrev_i32_e32 v33, 31, v32
	v_lshlrev_b64 v[34:35], 10, v[32:33]
	v_lshl_add_u64 v[40:41], v[34:35], 0, v[140:141]
	v_readlane_b32 s76, v252, 6
	v_lshlrev_b64 v[42:43], 2, v[40:41]
	v_readlane_b32 s77, v252, 7
	v_readlane_b32 s78, v252, 8
	v_readlane_b32 s79, v252, 9
	v_lshl_add_u64 v[34:35], s[76:77], 0, v[42:43]
	global_load_dwordx4 v[36:39], v[34:35], off
	v_readlane_b32 s80, v252, 10
	v_readlane_b32 s81, v252, 11
	v_readlane_b32 s82, v252, 12
	v_readlane_b32 s83, v252, 13
	v_readlane_b32 s84, v252, 14
	v_readlane_b32 s85, v252, 15
	v_readlane_b32 s86, v252, 16
	v_readlane_b32 s87, v252, 17
	v_readlane_b32 s88, v252, 18
	v_readlane_b32 s89, v252, 19
	v_readlane_b32 s90, v252, 20
	v_readlane_b32 s91, v252, 21
	s_waitcnt vmcnt(0)
	v_pk_add_f32 v[38:39], v[30:31], v[38:39]
	v_pk_add_f32 v[36:37], v[28:29], v[36:37]
	v_lshl_add_u64 v[28:29], s[56:57], 0, v[42:43]
	global_store_dwordx4 v[28:29], v[36:39], off
	v_cvt_pk_bf16_f32 v160, v36, v37
	v_lshlrev_b64 v[30:31], 1, v[40:41]
	v_mul_f32_e32 v37, v37, v37
	v_cvt_pk_bf16_f32 v161, v38, v39
	v_lshl_add_u64 v[40:41], s[62:63], 0, v[30:31]
	v_fmac_f32_e32 v37, v36, v36
	v_mul_f32_e32 v36, v39, v39
	v_fmac_f32_e32 v36, v38, v38
	v_add_f32_e32 v40, v37, v36
	global_load_dwordx4 v[36:39], v[34:35], off offset:16
	s_waitcnt vmcnt(0)
	v_pk_add_f32 v[26:27], v[26:27], v[38:39]
	v_pk_add_f32 v[24:25], v[24:25], v[36:37]
	global_store_dwordx4 v[28:29], v[24:27], off offset:16
	v_cvt_pk_bf16_f32 v162, v24, v25
	v_or_b32_e32 v38, 8, v30
	v_mul_f32_e32 v25, v25, v25
	v_mov_b32_e32 v39, v31
	v_fmac_f32_e32 v25, v24, v24
	v_mul_f32_e32 v24, v27, v27
	v_cvt_pk_bf16_f32 v163, v26, v27
	v_lshl_add_u64 v[38:39], s[62:63], 0, v[38:39]
	v_fmac_f32_e32 v24, v26, v26
	global_store_dwordx4 v[38:39], v[160:163], off offset:-8
	v_add_f32_e32 v24, v25, v24
	v_add_f32_e32 v36, v40, v24
	global_load_dwordx4 v[24:27], v[34:35], off offset:512
	s_waitcnt vmcnt(0)
	v_pk_add_f32 v[22:23], v[22:23], v[26:27]
	v_pk_add_f32 v[20:21], v[20:21], v[24:25]
	global_store_dwordx4 v[28:29], v[20:23], off offset:512
	v_cvt_pk_bf16_f32 v164, v20, v21
	v_or_b32_e32 v26, 0x100, v30
	v_mul_f32_e32 v21, v21, v21
	v_mov_b32_e32 v27, v31
	v_fmac_f32_e32 v21, v20, v20
	v_mul_f32_e32 v20, v23, v23
	v_cvt_pk_bf16_f32 v165, v22, v23
	v_lshl_add_u64 v[26:27], s[62:63], 0, v[26:27]
	v_fmac_f32_e32 v20, v22, v22
	v_add_f32_e32 v20, v21, v20
	v_add_f32_e32 v24, v36, v20
	global_load_dwordx4 v[20:23], v[34:35], off offset:528
	v_or_b32_e32 v30, 0x108, v30
	s_waitcnt vmcnt(0)
	v_pk_add_f32 v[18:19], v[18:19], v[22:23]
	v_pk_add_f32 v[16:17], v[16:17], v[20:21]
	global_store_dwordx4 v[28:29], v[16:19], off offset:528
	v_cvt_pk_bf16_f32 v166, v16, v17
	v_cvt_pk_bf16_f32 v167, v18, v19
	v_mul_f32_e32 v17, v17, v17
	v_fmac_f32_e32 v17, v16, v16
	v_mul_f32_e32 v16, v19, v19
	v_fmac_f32_e32 v16, v18, v18
	v_add_f32_e32 v16, v17, v16
	v_add_f32_e32 v16, v24, v16
	ds_bpermute_b32 v17, v149, v16
	v_lshl_add_u64 v[22:23], s[62:63], 0, v[30:31]
	global_store_dwordx4 v[22:23], v[164:167], off offset:-8
	s_waitcnt lgkmcnt(0)
	v_add_f32_e32 v16, v16, v17
	ds_bpermute_b32 v17, v148, v16
	s_and_saveexec_b64 s[46:47], s[36:37]
	s_cbranch_execz .LBB0_1077
	v_lshlrev_b64 v[18:19], 6, v[32:33]
	v_lshl_add_u64 v[18:19], s[54:55], 0, v[18:19]
	v_lshl_add_u64 v[18:19], s[0:1], 2, v[18:19]
	s_lshl_b32 s92, s18, 2
	v_lshl_add_u64 v[18:19], v[18:19], 0, s[92:93]
	s_waitcnt lgkmcnt(0)
	v_add_f32_e32 v16, v16, v17
	global_store_dword v[18:19], v16, off
.LBB0_1077:
	s_or_b64 exec, exec, s[46:47]
	v_add_u32_e32 v16, 0xb0, v142
	s_waitcnt lgkmcnt(0)
	v_ashrrev_i32_e32 v17, 31, v16
	v_lshlrev_b64 v[18:19], 10, v[16:17]
	v_lshl_add_u64 v[24:25], v[18:19], 0, v[140:141]
	v_readlane_b32 s76, v252, 6
	v_lshlrev_b64 v[26:27], 2, v[24:25]
	v_readlane_b32 s77, v252, 7
	v_readlane_b32 s80, v252, 10
	v_readlane_b32 s81, v252, 11
	v_lshl_add_u64 v[18:19], s[76:77], 0, v[26:27]
	global_load_dwordx4 v[20:23], v[18:19], off
	v_readlane_b32 s82, v252, 12
	v_readlane_b32 s83, v252, 13
	s_mov_b64 s[82:83], s[58:59]
	s_mov_b64 s[80:81], s[56:57]
	v_readlane_b32 s78, v252, 8
	v_readlane_b32 s79, v252, 9
	v_readlane_b32 s84, v252, 14
	v_readlane_b32 s85, v252, 15
	v_readlane_b32 s86, v252, 16
	v_readlane_b32 s87, v252, 17
	v_readlane_b32 s88, v252, 18
	v_readlane_b32 s89, v252, 19
	v_readlane_b32 s90, v252, 20
	v_readlane_b32 s91, v252, 21
	s_waitcnt vmcnt(0)
	v_pk_add_f32 v[22:23], v[14:15], v[22:23]
	v_pk_add_f32 v[20:21], v[12:13], v[20:21]
	v_lshl_add_u64 v[12:13], s[80:81], 0, v[26:27]
	global_store_dwordx4 v[12:13], v[20:23], off
	v_cvt_pk_bf16_f32 v160, v20, v21
	v_lshlrev_b64 v[14:15], 1, v[24:25]
	v_mul_f32_e32 v21, v21, v21
	v_cvt_pk_bf16_f32 v161, v22, v23
	v_lshl_add_u64 v[24:25], s[62:63], 0, v[14:15]
	v_fmac_f32_e32 v21, v20, v20
	v_mul_f32_e32 v20, v23, v23
	v_fmac_f32_e32 v20, v22, v22
	v_add_f32_e32 v24, v21, v20
	global_load_dwordx4 v[20:23], v[18:19], off offset:16
	s_waitcnt vmcnt(0)
	v_pk_add_f32 v[10:11], v[10:11], v[22:23]
	v_pk_add_f32 v[8:9], v[8:9], v[20:21]
	global_store_dwordx4 v[12:13], v[8:11], off offset:16
	v_cvt_pk_bf16_f32 v162, v8, v9
	v_or_b32_e32 v22, 8, v14
	v_mul_f32_e32 v9, v9, v9
	v_mov_b32_e32 v23, v15
	v_fmac_f32_e32 v9, v8, v8
	v_mul_f32_e32 v8, v11, v11
	v_cvt_pk_bf16_f32 v163, v10, v11
	v_lshl_add_u64 v[22:23], s[62:63], 0, v[22:23]
	v_fmac_f32_e32 v8, v10, v10
	global_store_dwordx4 v[22:23], v[160:163], off offset:-8
	v_add_f32_e32 v8, v9, v8
	v_add_f32_e32 v20, v24, v8
	global_load_dwordx4 v[8:11], v[18:19], off offset:512
	s_waitcnt vmcnt(0)
	v_pk_add_f32 v[6:7], v[6:7], v[10:11]
	v_pk_add_f32 v[4:5], v[4:5], v[8:9]
	global_store_dwordx4 v[12:13], v[4:7], off offset:512
	v_cvt_pk_bf16_f32 v164, v4, v5
	v_or_b32_e32 v10, 0x100, v14
	v_mul_f32_e32 v5, v5, v5
	v_mov_b32_e32 v11, v15
	v_fmac_f32_e32 v5, v4, v4
	v_mul_f32_e32 v4, v7, v7
	v_cvt_pk_bf16_f32 v165, v6, v7
	v_lshl_add_u64 v[10:11], s[62:63], 0, v[10:11]
	v_fmac_f32_e32 v4, v6, v6
	v_add_f32_e32 v4, v5, v4
	v_add_f32_e32 v8, v20, v4
	global_load_dwordx4 v[4:7], v[18:19], off offset:528
	v_or_b32_e32 v14, 0x108, v14
	s_waitcnt vmcnt(0)
	v_pk_add_f32 v[2:3], v[2:3], v[6:7]
	v_pk_add_f32 v[0:1], v[0:1], v[4:5]
	global_store_dwordx4 v[12:13], v[0:3], off offset:528
	v_cvt_pk_bf16_f32 v166, v0, v1
	v_cvt_pk_bf16_f32 v167, v2, v3
	v_mul_f32_e32 v1, v1, v1
	v_fmac_f32_e32 v1, v0, v0
	v_mul_f32_e32 v0, v3, v3
	v_fmac_f32_e32 v0, v2, v2
	v_add_f32_e32 v0, v1, v0
	v_add_f32_e32 v0, v8, v0
	ds_bpermute_b32 v1, v149, v0
	v_lshl_add_u64 v[6:7], s[62:63], 0, v[14:15]
	global_store_dwordx4 v[6:7], v[164:167], off offset:-8
	s_waitcnt lgkmcnt(0)
	v_add_f32_e32 v0, v0, v1
	ds_bpermute_b32 v1, v148, v0
	s_and_saveexec_b64 s[46:47], s[36:37]
	s_cbranch_execz .LBB0_1079
	v_lshlrev_b64 v[2:3], 6, v[16:17]
	v_lshl_add_u64 v[2:3], s[54:55], 0, v[2:3]
	v_lshl_add_u64 v[2:3], s[0:1], 2, v[2:3]
	s_lshl_b32 s92, s18, 2
	v_lshl_add_u64 v[2:3], v[2:3], 0, s[92:93]
	s_waitcnt lgkmcnt(0)
	v_add_f32_e32 v0, v0, v1
	global_store_dword v[2:3], v0, off
